# mixB1 conv prologue: the 4 taps' activation/weight loads issued up front (clamped row index, masked FMAs, counted waits) instead of one load round trip per tap; on top of v21
# baseline (speedup 1.0000x reference)
; __device__ __forceinline__ void mixB1_item(const Params& P, int layer, int idx, const bf16_t* z, float* hsl, float* Pc, float* carryP, float* carryH, char* lds) {
;     ...
;   {
;     const int t = tid >> 2, q = tid & 3;
;     float accv[16];
; #pragma unroll
;     for (int i = 0; i < 16; ++i) accv[i] = P.conv_b[layer * 256 + g * 64 + q * 16 + i];
; #pragma unroll
;     for (int k = 0; k < 4; ++k) {
;       const int pos = c * 64 + t - 3 + k;
;       if (pos >= 0) {
;         const bf16_t* zr = z + (tokb + pos) * LDZ + ZC_BX + g * 64 + q * 16;
;         float v[16]; unpack8(*(const u32x4*)zr, v); unpack8(*(const u32x4*)(zr + 8), v + 8);
;         const float* cw = P.conv_w + (size_t)(layer * 4 + k) * 256 + g * 64 + q * 16;
; #pragma unroll
;         for (int i = 0; i < 16; ++i) accv[i] += v[i] * cw[i];
;       }
;     }
.LBB0_556:
	s_waitcnt vmcnt(0)
	v_bfe_u32 v30, v61, 6, 2
	v_mov_b32 v43, v179
	v_lshlrev_b32_e32 v35, 6, v30
	v_lshlrev_b32_e32 v0, 4, v43
	v_or_b32_e32 v42, s16, v35
	v_and_b32_e32 v19, 48, v0
	v_or_b32_e32 v0, v42, v19
	v_readlane_b32 s60, v252, 2
	v_lshlrev_b32_e32 v12, 2, v0
	v_readlane_b32 s70, v252, 12
	v_readlane_b32 s71, v252, 13
	s_nop 4
	global_load_dwordx4 v[0:3], v12, s[70:71] offset:48
	global_load_dwordx4 v[4:7], v12, s[70:71] offset:32
	global_load_dwordx4 v[8:11], v12, s[70:71] offset:16
	s_nop 0
	global_load_dwordx4 v[12:15], v12, s[70:71]
	v_ashrrev_i32_e32 v16, 8, v61
	v_and_b32_e32 v36, 63, v61
	v_ashrrev_i32_e32 v17, 31, v16
	v_bfe_u32 v24, v43, 2, 6
	v_lshlrev_b32_e32 v37, 6, v36
	v_readlane_b32 s68, v252, 10
	v_readlane_b32 s69, v252, 11
	v_lshlrev_b64 v[32:33], 12, v[16:17]
	v_or_b32_e32 v16, v37, v24
	v_lshlrev_b32_e32 v176, 8, v30
	v_add_u32_e32 v20, -3, v16
	v_lshl_add_u64 v[16:17], s[68:69], 0, v[176:177]
	v_lshlrev_b32_e32 v176, 2, v19
	v_lshl_add_u64 v[16:17], v[16:17], 0, v[176:177]
	v_cmp_lt_i32_e32 vcc, -1, v20
	v_lshl_add_u64 v[28:29], v[16:17], 0, s[46:47]
	v_lshlrev_b32_e32 v18, 1, v35
	v_lshlrev_b32_e32 v16, 1, v19
	v_readlane_b32 s61, v252, 3
	v_readlane_b32 s62, v252, 4
	v_readlane_b32 s63, v252, 5
	v_readlane_b32 s64, v252, 6
	v_readlane_b32 s65, v252, 7
	v_readlane_b32 s66, v252, 8
	v_readlane_b32 s67, v252, 9
	v_readlane_b32 s72, v252, 14
	v_readlane_b32 s73, v252, 15
	v_readlane_b32 s74, v252, 16
	v_readlane_b32 s75, v252, 17
	s_movk_i32 s39, 0x1400
	s_movk_i32 s38, 0x7fff
	v_mov_b32_e32 v84, v20
	v_mov_b32_e32 v88, v18
	v_mov_b32_e32 v89, v177
	v_mov_b32_e32 v90, v16
	v_mov_b32_e32 v91, v177
	v_max_i32_e32 v86, 0, v84
	v_mov_b32_e32 v87, v177
	v_lshl_add_u64 v[86:87], v[32:33], 0, v[86:87]
	v_mov_b64_e32 v[92:93], s[84:85]
	v_mad_u64_u32 v[92:93], s[30:31], v86, s39, v[92:93]
	v_mad_i32_i24 v93, v87, s39, v93
	v_lshl_add_u64 v[92:93], v[92:93], 0, v[88:89]
	v_lshl_add_u64 v[92:93], v[92:93], 0, v[90:91]
	global_load_dwordx4 v[108:111], v[92:93], off offset:1040
	global_load_dwordx4 v[104:107], v[92:93], off offset:1024
	global_load_dwordx4 v[124:127], v[28:29], off offset:48
	global_load_dwordx4 v[120:123], v[28:29], off offset:32
	global_load_dwordx4 v[116:119], v[28:29], off offset:16
	global_load_dwordx4 v[112:115], v[28:29], off offset:0
	v_add_u32_e32 v86, 1, v84
	v_max_i32_e32 v86, 0, v86
	v_mov_b32_e32 v87, v177
	v_lshl_add_u64 v[86:87], v[32:33], 0, v[86:87]
	v_mov_b64_e32 v[94:95], s[84:85]
	v_mad_u64_u32 v[94:95], s[30:31], v86, s39, v[94:95]
	v_mad_i32_i24 v95, v87, s39, v95
	v_lshl_add_u64 v[94:95], v[94:95], 0, v[88:89]
	v_lshl_add_u64 v[94:95], v[94:95], 0, v[90:91]
	global_load_dwordx4 v[132:135], v[94:95], off offset:1040
	global_load_dwordx4 v[128:131], v[94:95], off offset:1024
	global_load_dwordx4 v[148:151], v[28:29], off offset:1072
	global_load_dwordx4 v[144:147], v[28:29], off offset:1056
	global_load_dwordx4 v[140:143], v[28:29], off offset:1040
	global_load_dwordx4 v[136:139], v[28:29], off offset:1024
	v_add_u32_e32 v86, 2, v84
	v_max_i32_e32 v86, 0, v86
	v_mov_b32_e32 v87, v177
	v_lshl_add_u64 v[86:87], v[32:33], 0, v[86:87]
	v_mov_b64_e32 v[96:97], s[84:85]
	v_mad_u64_u32 v[96:97], s[30:31], v86, s39, v[96:97]
	v_mad_i32_i24 v97, v87, s39, v97
	v_lshl_add_u64 v[96:97], v[96:97], 0, v[88:89]
	v_lshl_add_u64 v[96:97], v[96:97], 0, v[90:91]
	global_load_dwordx4 v[156:159], v[96:97], off offset:1040
	global_load_dwordx4 v[152:155], v[96:97], off offset:1024
	global_load_dwordx4 v[172:175], v[28:29], off offset:2096
	global_load_dwordx4 v[168:171], v[28:29], off offset:2080
	global_load_dwordx4 v[164:167], v[28:29], off offset:2064
	global_load_dwordx4 v[160:163], v[28:29], off offset:2048
	v_or3_b32 v17, v24, v37, v32
	v_mov_b64_e32 v[20:21], s[84:85]
	v_mad_u64_u32 v[20:21], s[0:1], v17, s39, v[20:21]
	v_mad_i32_i24 v21, v33, s39, v21
	v_mov_b32_e32 v19, v177
	v_lshl_add_u64 v[18:19], v[20:21], 0, v[18:19]
	v_mov_b32_e32 v17, v177
	v_lshl_add_u64 v[18:19], v[18:19], 0, v[16:17]
	v_mul_u32_u24_e32 v17, 0x104, v24
	global_load_dwordx4 v[20:23], v[18:19], off offset:1040
	global_load_dwordx4 v[44:47], v[18:19], off offset:1024
	v_add3_u32 v56, v60, v17, v176
	v_mul_u32_u24_e32 v17, 0x90, v24
	v_add3_u32 v41, v60, v17, v16
	global_load_dwordx4 v[16:19], v[28:29], off offset:3120
	global_load_dwordx4 v[24:27], v[28:29], off offset:3104
	global_load_dwordx4 v[48:51], v[28:29], off offset:3088
	global_load_dwordx4 v[52:55], v[28:29], off offset:3072
	v_cmp_lt_i32_e32 vcc, -1, v84
	s_and_saveexec_b64 s[0:1], vcc
	s_waitcnt vmcnt(18)
	v_lshlrev_b32_e32 v98, 16, v104
	v_and_b32_e32 v99, 0xffff0000, v104
	v_pk_fma_f32 v[12:13], v[112:113], v[98:99], v[12:13]
	v_lshlrev_b32_e32 v100, 16, v105
	v_and_b32_e32 v101, 0xffff0000, v105
	v_pk_fma_f32 v[14:15], v[114:115], v[100:101], v[14:15]
	v_lshlrev_b32_e32 v98, 16, v106
	v_and_b32_e32 v99, 0xffff0000, v106
	v_pk_fma_f32 v[8:9], v[116:117], v[98:99], v[8:9]
	v_lshlrev_b32_e32 v100, 16, v107
	v_and_b32_e32 v101, 0xffff0000, v107
	v_pk_fma_f32 v[10:11], v[118:119], v[100:101], v[10:11]
	v_lshlrev_b32_e32 v98, 16, v108
	v_and_b32_e32 v99, 0xffff0000, v108
	v_pk_fma_f32 v[4:5], v[120:121], v[98:99], v[4:5]
	v_lshlrev_b32_e32 v100, 16, v109
	v_and_b32_e32 v101, 0xffff0000, v109
	v_pk_fma_f32 v[6:7], v[122:123], v[100:101], v[6:7]
	v_lshlrev_b32_e32 v98, 16, v110
	v_and_b32_e32 v99, 0xffff0000, v110
	v_pk_fma_f32 v[0:1], v[124:125], v[98:99], v[0:1]
	v_lshlrev_b32_e32 v100, 16, v111
	v_and_b32_e32 v101, 0xffff0000, v111
	v_pk_fma_f32 v[2:3], v[126:127], v[100:101], v[2:3]
	s_or_b64 exec, exec, s[0:1]
	v_cmp_lt_i32_e32 vcc, -2, v84
	s_and_saveexec_b64 s[0:1], vcc
	s_waitcnt vmcnt(12)
; __device__ __forceinline__ bf16_t f2bf(float f) { unsigned u = __float_as_uint(f); u += 0x7fffu + ((u >> 16) & 1u); return (bf16_t)(u >> 16); }
; __device__ __forceinline__ void mixB1_item(const Params& P, int layer, int idx, const bf16_t* z, float* hsl, float* Pc, float* carryP, float* carryH, char* lds) {
;     ...
; #pragma unroll
;     for (int k = 0; k < 4; ++k) {
;       const int pos = c * 64 + t - 3 + k;
;       if (pos >= 0) {
;         const bf16_t* zr = z + (tokb + pos) * LDZ + ZC_BX + g * 64 + q * 16;
;         float v[16]; unpack8(*(const u32x4*)zr, v); unpack8(*(const u32x4*)(zr + 8), v + 8);
;         const float* cw = P.conv_w + (size_t)(layer * 4 + k) * 256 + g * 64 + q * 16;
; #pragma unroll
;         for (int i = 0; i < 16; ++i) accv[i] += v[i] * cw[i];
;       }
;     }
; #pragma unroll
;     for (int i = 0; i < 16; ++i) { xcf[t * 65 + q * 16 + i] = accv[i]; xcb[t * 72 + q * 16 + i] = f2bf(accv[i]); }
	v_lshlrev_b32_e32 v98, 16, v128
	v_and_b32_e32 v99, 0xffff0000, v128
	v_pk_fma_f32 v[12:13], v[136:137], v[98:99], v[12:13]
	v_lshlrev_b32_e32 v100, 16, v129
	v_and_b32_e32 v101, 0xffff0000, v129
	v_pk_fma_f32 v[14:15], v[138:139], v[100:101], v[14:15]
	v_lshlrev_b32_e32 v98, 16, v130
	v_and_b32_e32 v99, 0xffff0000, v130
	v_pk_fma_f32 v[8:9], v[140:141], v[98:99], v[8:9]
	v_lshlrev_b32_e32 v100, 16, v131
	v_and_b32_e32 v101, 0xffff0000, v131
	v_pk_fma_f32 v[10:11], v[142:143], v[100:101], v[10:11]
	v_lshlrev_b32_e32 v98, 16, v132
	v_and_b32_e32 v99, 0xffff0000, v132
	v_pk_fma_f32 v[4:5], v[144:145], v[98:99], v[4:5]
	v_lshlrev_b32_e32 v100, 16, v133
	v_and_b32_e32 v101, 0xffff0000, v133
	v_pk_fma_f32 v[6:7], v[146:147], v[100:101], v[6:7]
	v_lshlrev_b32_e32 v98, 16, v134
	v_and_b32_e32 v99, 0xffff0000, v134
	v_pk_fma_f32 v[0:1], v[148:149], v[98:99], v[0:1]
	v_lshlrev_b32_e32 v100, 16, v135
	v_and_b32_e32 v101, 0xffff0000, v135
	v_pk_fma_f32 v[2:3], v[150:151], v[100:101], v[2:3]
	s_or_b64 exec, exec, s[0:1]
	v_cmp_lt_i32_e32 vcc, -3, v84
	s_and_saveexec_b64 s[0:1], vcc
	s_waitcnt vmcnt(6)
	v_lshlrev_b32_e32 v98, 16, v152
	v_and_b32_e32 v99, 0xffff0000, v152
	v_pk_fma_f32 v[12:13], v[160:161], v[98:99], v[12:13]
	v_lshlrev_b32_e32 v100, 16, v153
	v_and_b32_e32 v101, 0xffff0000, v153
	v_pk_fma_f32 v[14:15], v[162:163], v[100:101], v[14:15]
	v_lshlrev_b32_e32 v98, 16, v154
	v_and_b32_e32 v99, 0xffff0000, v154
	v_pk_fma_f32 v[8:9], v[164:165], v[98:99], v[8:9]
	v_lshlrev_b32_e32 v100, 16, v155
	v_and_b32_e32 v101, 0xffff0000, v155
	v_pk_fma_f32 v[10:11], v[166:167], v[100:101], v[10:11]
	v_lshlrev_b32_e32 v98, 16, v156
	v_and_b32_e32 v99, 0xffff0000, v156
	v_pk_fma_f32 v[4:5], v[168:169], v[98:99], v[4:5]
	v_lshlrev_b32_e32 v100, 16, v157
	v_and_b32_e32 v101, 0xffff0000, v157
	v_pk_fma_f32 v[6:7], v[170:171], v[100:101], v[6:7]
	v_lshlrev_b32_e32 v98, 16, v158
	v_and_b32_e32 v99, 0xffff0000, v158
	v_pk_fma_f32 v[0:1], v[172:173], v[98:99], v[0:1]
	v_lshlrev_b32_e32 v100, 16, v159
	v_and_b32_e32 v101, 0xffff0000, v159
	v_pk_fma_f32 v[2:3], v[174:175], v[100:101], v[2:3]
	s_or_b64 exec, exec, s[0:1]
	v_add_u32_e32 v57, 0x2400, v56
	s_mov_b32 s0, 0x7060302
	v_and_b32_e32 v40, 0xff, v43
	v_lshrrev_b32_e32 v39, 6, v40
	v_and_b32_e32 v31, 15, v43
	v_lshl_or_b32 v176, v30, 13, s17
	v_mov_b32_e32 v69, v177
	v_and_b32_e32 v38, 63, v43
	v_readlane_b32 s64, v252, 2
	v_readlane_b32 s65, v252, 3
	v_readlane_b32 s66, v252, 4
	v_readlane_b32 s67, v252, 5
	v_readlane_b32 s68, v252, 6
	v_readlane_b32 s69, v252, 7
	v_readlane_b32 s70, v252, 8
	v_readlane_b32 s71, v252, 9
	v_readlane_b32 s72, v252, 10
	v_readlane_b32 s73, v252, 11
	v_readlane_b32 s74, v252, 12
	v_readlane_b32 s75, v252, 13
	v_readlane_b32 s60, v252, 18
	v_readlane_b32 s78, v252, 16
	v_readlane_b32 s79, v252, 17
	v_readlane_b32 s62, v252, 20
	v_readlane_b32 s63, v252, 21
	v_readlane_b32 s64, v252, 22
	v_readlane_b32 s65, v252, 23
	s_mov_b32 s30, 0xbeaaaaab
	s_mov_b32 s31, 0xf800000
	v_readlane_b32 s76, v252, 14
	v_readlane_b32 s77, v252, 15
	v_readlane_b32 s61, v252, 19
	v_readlane_b32 s66, v252, 24
	v_readlane_b32 s67, v252, 25
	v_readlane_b32 s68, v252, 26
	v_readlane_b32 s69, v252, 27
	v_readlane_b32 s70, v252, 28
	v_readlane_b32 s71, v252, 29
	v_readlane_b32 s72, v252, 30
	v_readlane_b32 s73, v252, 31
	v_readlane_b32 s74, v252, 32
	v_readlane_b32 s75, v252, 33
	s_waitcnt vmcnt(0)
	v_lshlrev_b32_e32 v28, 16, v44
	v_and_b32_e32 v29, 0xffff0000, v44
	v_add_u32_e32 v44, 0x2408, v56
	v_pk_fma_f32 v[12:13], v[52:53], v[28:29], v[12:13]
	v_lshlrev_b32_e32 v28, 16, v45
	v_and_b32_e32 v29, 0xffff0000, v45
	v_pk_fma_f32 v[14:15], v[54:55], v[28:29], v[14:15]
	ds_write2_b32 v44, v14, v15 offset1:1
	v_bfe_u32 v28, v15, 16, 1
	v_bfe_u32 v29, v14, 16, 1
	v_bfe_u32 v44, v13, 16, 1
	v_bfe_u32 v45, v12, 16, 1
	ds_write2_b32 v57, v12, v13 offset1:1
	v_add3_u32 v14, v14, v29, s38
	v_add3_u32 v15, v15, v28, s38
	v_add3_u32 v28, v12, v45, s38
	v_add3_u32 v29, v13, v44, s38
	v_lshlrev_b32_e32 v12, 16, v46
	v_and_b32_e32 v13, 0xffff0000, v46
	v_add_u32_e32 v44, 0x2410, v56
	v_pk_fma_f32 v[8:9], v[48:49], v[12:13], v[8:9]
	v_lshlrev_b32_e32 v12, 16, v47
	v_and_b32_e32 v13, 0xffff0000, v47
	ds_write2_b32 v44, v8, v9 offset1:1
	v_add_u32_e32 v44, 0x2418, v56
	v_pk_fma_f32 v[10:11], v[50:51], v[12:13], v[10:11]
	ds_write2_b32 v44, v10, v11 offset1:1
	v_bfe_u32 v12, v11, 16, 1
	v_bfe_u32 v13, v10, 16, 1
	v_bfe_u32 v44, v9, 16, 1
	v_bfe_u32 v45, v8, 16, 1
	v_add3_u32 v10, v10, v13, s38
	v_add3_u32 v11, v11, v12, s38
	v_add3_u32 v8, v8, v45, s38
	v_add3_u32 v12, v9, v44, s38
	v_perm_b32 v11, v11, v10, s0
	v_perm_b32 v9, v15, v14, s0
	v_perm_b32 v10, v12, v8, s0
	v_perm_b32 v8, v29, v28, s0
	ds_write_b128 v41, v[8:11]
	v_lshlrev_b32_e32 v8, 16, v20
	v_and_b32_e32 v9, 0xffff0000, v20
	v_add_u32_e32 v10, 0x2420, v56
	v_pk_fma_f32 v[4:5], v[24:25], v[8:9], v[4:5]
	v_lshlrev_b32_e32 v8, 16, v21
	v_and_b32_e32 v9, 0xffff0000, v21
	ds_write2_b32 v10, v4, v5 offset1:1
	v_add_u32_e32 v10, 0x2428, v56
	v_pk_fma_f32 v[6:7], v[26:27], v[8:9], v[6:7]
	ds_write2_b32 v10, v6, v7 offset1:1
	v_bfe_u32 v8, v7, 16, 1
	v_bfe_u32 v9, v6, 16, 1
	v_bfe_u32 v10, v5, 16, 1
	v_bfe_u32 v11, v4, 16, 1
	v_add3_u32 v6, v6, v9, s38
	v_add3_u32 v7, v7, v8, s38
	v_add3_u32 v8, v4, v11, s38
	v_add3_u32 v9, v5, v10, s38
	v_lshlrev_b32_e32 v4, 16, v22
	v_and_b32_e32 v5, 0xffff0000, v22
	v_add_u32_e32 v10, 0x2430, v56
	v_pk_fma_f32 v[0:1], v[16:17], v[4:5], v[0:1]
	v_lshlrev_b32_e32 v4, 16, v23
	v_and_b32_e32 v5, 0xffff0000, v23
	ds_write2_b32 v10, v0, v1 offset1:1
	v_add_u32_e32 v10, 0x2438, v56
	v_pk_fma_f32 v[2:3], v[18:19], v[4:5], v[2:3]
	ds_write2_b32 v10, v2, v3 offset1:1
	v_bfe_u32 v4, v3, 16, 1
	v_bfe_u32 v5, v2, 16, 1
	v_bfe_u32 v10, v1, 16, 1
	v_bfe_u32 v11, v0, 16, 1
	v_add3_u32 v2, v2, v5, s38
	v_add3_u32 v3, v3, v4, s38
	v_add3_u32 v0, v0, v11, s38
	v_add3_u32 v4, v1, v10, s38
	v_perm_b32 v3, v3, v2, s0
	v_perm_b32 v1, v7, v6, s0
	v_perm_b32 v2, v4, v0, s0
	v_perm_b32 v0, v9, v8, s0
	ds_write_b128 v41, v[0:3] offset:16
	v_lshlrev_b32_e32 v41, 4, v39
	v_or_b32_e32 v72, v41, v31
	v_lshl_add_u64 v[0:1], s[88:89], 0, v[176:177]
	v_lshl_add_u64 v[2:3], s[90:91], 0, v[176:177]
	v_mul_u32_u24_e32 v4, 0x90, v72
	v_and_b32_e32 v176, 48, v43
	v_add3_u32 v30, v60, v4, v176
	v_lshl_add_u64 v[28:29], v[0:1], 0, v[176:177]
	v_lshl_add_u64 v[62:63], v[2:3], 0, v[176:177]
	v_lshlrev_b32_e32 v176, 7, v31
	v_or_b32_e32 v68, 0x1000, v176
	v_lshl_add_u64 v[64:65], v[28:29], 0, v[176:177]
	v_lshl_add_u64 v[66:67], v[62:63], 0, v[176:177]
	v_lshl_add_u64 v[20:21], v[28:29], 0, v[68:69]
	v_lshl_add_u64 v[24:25], v[62:63], 0, v[68:69]
	s_waitcnt lgkmcnt(0)
	s_barrier
; __device__ __forceinline__ float sigm(float x) { return __builtin_amdgcn_rcpf(1.f + __expf(-x)); }
; __device__ __forceinline__ f32x4 mfma16(bf16x8 a, bf16x8 b, f32x4 c) { return __builtin_amdgcn_mfma_f32_16x16x32_bf16(a, b, c, 0, 0, 0); }
; __device__ __forceinline__ void mixB1_item(const Params& P, int layer, int idx, const bf16_t* z, float* hsl, float* Pc, float* carryP, float* carryH, char* lds) {
;     ...
;     f32x4 ar[4] = {}, ai[4] = {};
; #pragma unroll
;     for (int ks = 0; ks < 2; ++ks) {
;       const bf16x8 xf = *(const bf16x8*)(xcb + (16 * w + fr) * 72 + ks * 32 + 8 * fq);
; #pragma unroll
;       for (int jn = 0; jn < 4; ++jn) {
;         const bf16x8 fa = *(const bf16x8*)(wa + (jn * 16 + fr) * 64 + ks * 32 + 8 * fq);
;         const bf16x8 fx = *(const bf16x8*)(wx + (jn * 16 + fr) * 64 + ks * 32 + 8 * fq);
;         ar[jn] = mfma16(fa, xf, ar[jn]); ai[jn] = mfma16(fx, xf, ai[jn]);
;       }
;     }
;     const int t = 16 * w + fr;
; #pragma unroll
;     for (int jn = 0; jn < 4; ++jn)
; #pragma unroll
;       for (int e = 0; e < 4; ++e) {
;         const int j = jn * 16 + 4 * fq + e, ch = layer * 256 + g * 64 + j;
;         const float r = sigm(ar[jn][e] + P.lru_ba[ch]), ig = sigm(ai[jn][e] + P.lru_bx[ch]);
;         const float lam = P.lru_lam[ch];
;         const float xe = __expf(-lam);
;         float m8; asm volatile("v_mov_b32 %0, 0xc1000000" : "=v"(m8));
;         const float la = m8 * r * (xe * (1.f - xe * (0.5f - xe * (1.f / 3.f))));
;         const float av = __expf(la);
;         const float y2 = 2.f * la;
;         const float om = -y2 * (1.f + y2 * (0.5f + y2 * ((1.f / 6.f) + y2 * ((1.f / 24.f) + y2 * ((1.f / 120.f) + y2 * (1.f / 720.f))))));
;         const float bv = sqrtf(om) * (ig * xcf[t * 65 + j]);
;         aA[t * 65 + j] = av; bB[t * 65 + j] = bv;
;       }
	v_lshrrev_b32_e32 v73, 2, v179
	v_and_b32_e32 v73, 12, v73
	v_add_lshl_u32 v80, v73, v42, 2
	global_load_dwordx4 v[84:87], v80, s[78:79]
	global_load_dwordx4 v[88:91], v80, s[78:79] offset:64
	global_load_dwordx4 v[92:95], v80, s[78:79] offset:128
	global_load_dwordx4 v[96:99], v80, s[78:79] offset:192
	global_load_dwordx4 v[100:103], v80, s[62:63]
	global_load_dwordx4 v[104:107], v80, s[62:63] offset:64
	global_load_dwordx4 v[108:111], v80, s[62:63] offset:128
	global_load_dwordx4 v[112:115], v80, s[62:63] offset:192
	global_load_dwordx4 v[116:119], v80, s[64:65]
	global_load_dwordx4 v[120:123], v80, s[64:65] offset:64
	global_load_dwordx4 v[124:127], v80, s[64:65] offset:128
	global_load_dwordx4 v[128:131], v80, s[64:65] offset:192
	ds_read_b128 v[0:3], v30
	ds_read_b128 v[56:59], v30 offset:64
	v_add_co_u32_e32 v132, vcc, 0x1000, v64
	s_nop 1
	v_addc_co_u32_e32 v133, vcc, 0, v65, vcc
	v_add_co_u32_e32 v134, vcc, 0x1000, v66
	s_nop 1
	v_addc_co_u32_e32 v135, vcc, 0, v67, vcc
	global_load_dwordx4 v[136:139], v[64:65], off
	global_load_dwordx4 v[140:143], v[132:133], off
	global_load_dwordx4 v[144:147], v[134:135], off
	global_load_dwordx4 v[148:151], v[66:67], off
	global_load_dwordx4 v[152:155], v[64:65], off offset:2048
	global_load_dwordx4 v[156:159], v[66:67], off offset:2048
	global_load_dwordx4 v[160:163], v[132:133], off offset:2048
	global_load_dwordx4 v[164:167], v[134:135], off offset:2048
	global_load_dwordx4 v[168:171], v[64:65], off offset:64
	global_load_dwordx4 v[172:175], v[66:67], off offset:64
	global_load_dwordx4 v[180:183], v[64:65], off offset:2112
	global_load_dwordx4 v[184:187], v[66:67], off offset:2112
	global_load_dwordx4 v[188:191], v[132:133], off offset:64
	global_load_dwordx4 v[192:195], v[134:135], off offset:64
	global_load_dwordx4 v[196:199], v[134:135], off offset:2112
	global_load_dwordx4 v[200:203], v[132:133], off offset:2112
	v_lshrrev_b32_e32 v43, 2, v43
	v_and_b32_e32 v43, 12, v43
	s_waitcnt vmcnt(15) lgkmcnt(1)
	v_mfma_f32_16x16x32_bf16 v[4:7], v[136:139], v[0:3], 0
	s_waitcnt vmcnt(14)
	v_mfma_f32_16x16x32_bf16 v[44:47], v[140:143], v[0:3], 0
	s_waitcnt vmcnt(13)
	v_mfma_f32_16x16x32_bf16 v[48:51], v[144:147], v[0:3], 0
	s_waitcnt vmcnt(12)
	v_mfma_f32_16x16x32_bf16 v[8:11], v[148:151], v[0:3], 0
	s_waitcnt vmcnt(11)
	v_mfma_f32_16x16x32_bf16 v[12:15], v[152:155], v[0:3], 0
	s_waitcnt vmcnt(10)
	v_mfma_f32_16x16x32_bf16 v[16:19], v[156:159], v[0:3], 0
	s_waitcnt vmcnt(9)
	v_mfma_f32_16x16x32_bf16 v[52:55], v[160:163], v[0:3], 0
	s_waitcnt vmcnt(8)
	v_mfma_f32_16x16x32_bf16 v[0:3], v[164:167], v[0:3], 0
	s_waitcnt vmcnt(7) lgkmcnt(0)
	v_mfma_f32_16x16x32_bf16 v[28:31], v[168:171], v[56:59], v[4:7]
	s_waitcnt vmcnt(6)
	v_mfma_f32_16x16x32_bf16 v[24:27], v[172:175], v[56:59], v[8:11]
	s_waitcnt vmcnt(5)
	v_mfma_f32_16x16x32_bf16 v[20:23], v[180:183], v[56:59], v[12:15]
	s_waitcnt vmcnt(4)
	v_mfma_f32_16x16x32_bf16 v[16:19], v[184:187], v[56:59], v[16:19]
	s_waitcnt vmcnt(3)
	v_mfma_f32_16x16x32_bf16 v[12:15], v[188:191], v[56:59], v[44:47]
	s_waitcnt vmcnt(2)
	v_mfma_f32_16x16x32_bf16 v[8:11], v[192:195], v[56:59], v[48:51]
	s_waitcnt vmcnt(1)
	v_mfma_f32_16x16x32_bf16 v[0:3], v[196:199], v[56:59], v[0:3]
	v_or_b32_e32 v44, v43, v42
	v_lshlrev_b32_e32 v44, 2, v44
	v_mov_b32_e32 v45, v84
	v_mov_b32_e32 v46, v100
	v_add_lshl_u32 v42, v43, v42, 2
	s_waitcnt vmcnt(0)
	v_mfma_f32_16x16x32_bf16 v[4:7], v[200:203], v[56:59], v[52:55]
	s_waitcnt vmcnt(1)
	v_add_f32_e32 v28, v28, v45
	s_waitcnt vmcnt(0)
	v_add_f32_e32 v24, v24, v46
	v_mul_f32_e32 v24, 0xbfb8aa3b, v24
	v_exp_f32_e32 v24, v24
	v_mul_f32_e32 v28, 0xbfb8aa3b, v28
	v_exp_f32_e32 v45, v28
	v_mov_b32_e32 v28, 1.0
	v_add_f32_e32 v24, 1.0, v24
	v_rcp_f32_e32 v46, v24
	v_mov_b32_e32 v24, v116
	v_add_f32_e32 v45, 1.0, v45
	v_rcp_f32_e32 v45, v45
	v_mov_b32 v44, 0xc1000000
	s_waitcnt vmcnt(0)
	v_mul_f32_e32 v24, 0xbfb8aa3b, v24
	v_exp_f32_e32 v24, v24
	v_mul_f32_e32 v44, v44, v45
	v_fma_f32 v45, v24, s30, 0.5
	v_fma_f32 v45, -v24, v45, 1.0
	v_mul_f32_e32 v24, v24, v45
	v_mul_f32_e32 v24, v44, v24
	v_mul_f32_e32 v44, 0x3fb8aa3b, v24
	v_add_f32_e32 v24, v24, v24
	v_fmamk_f32 v45, v24, 0x3ab60b61, v213
	v_fmaak_f32 v45, v24, v45, 0x3d2aaaab
	v_fmaak_f32 v45, v24, v45, 0x3e2aaaab
	v_fma_f32 v45, v24, v45, 0.5
	v_fma_f32 v45, v24, v45, 1.0
	v_mul_f32_e64 v24, v45, -v24
	v_cmp_gt_f32_e32 vcc, s31, v24
	v_mul_f32_e32 v45, 0x4f800000, v24
	v_exp_f32_e32 v44, v44
	v_cndmask_b32_e32 v24, v24, v45, vcc
	v_sqrt_f32_e32 v45, v24
	s_nop 0
	v_add_u32_e32 v47, -1, v45
	v_fma_f32 v48, -v47, v45, v24
	v_cmp_ge_f32_e64 s[0:1], 0, v48
	v_add_u32_e32 v48, 1, v45
	s_nop 0
	v_cndmask_b32_e64 v47, v45, v47, s[0:1]
	v_fma_f32 v45, -v48, v45, v24
	v_cmp_lt_f32_e64 s[0:1], 0, v45
	s_nop 1
	v_cndmask_b32_e64 v45, v47, v48, s[0:1]
	v_mul_f32_e32 v47, 0x37800000, v45
	v_cndmask_b32_e32 v45, v45, v47, vcc
	v_cmp_class_f32_e32 vcc, v24, v214
	s_nop 1
	v_cndmask_b32_e32 v45, v45, v24, vcc
	v_mad_u32_u24 v24, v72, s33, v43
	v_mov_b32_e32 v43, v85
	v_lshl_add_u32 v24, v24, 2, v60
	ds_read_b32 v47, v24 offset:9216
	s_waitcnt lgkmcnt(0)
	v_mul_f32_e32 v46, v47, v46
	v_mul_f32_e32 v45, v46, v45
	ds_write2st64_b32 v24, v44, v45 offset0:101 offset1:166
	s_waitcnt vmcnt(0)
	v_add_f32_e32 v29, v29, v43
	v_mov_b32_e32 v43, v101
	v_mul_f32_e32 v29, 0xbfb8aa3b, v29
	v_exp_f32_e32 v29, v29
	s_waitcnt vmcnt(0)
	v_add_f32_e32 v25, v25, v43
	v_mov_b32_e32 v43, v117
	v_add_f32_e32 v29, 1.0, v29
	v_rcp_f32_e32 v29, v29
	v_mov_b32 v44, 0xc1000000
	v_mul_f32_e32 v25, 0xbfb8aa3b, v25
	v_exp_f32_e32 v25, v25
	v_mul_f32_e32 v29, v44, v29
	v_add_f32_e32 v25, 1.0, v25
	v_rcp_f32_e32 v25, v25
	s_waitcnt vmcnt(0)
; __device__ __forceinline__ float sigm(float x) { return __builtin_amdgcn_rcpf(1.f + __expf(-x)); }
; __device__ __forceinline__ void mixB1_item(const Params& P, int layer, int idx, const bf16_t* z, float* hsl, float* Pc, float* carryP, float* carryH, char* lds) {
;     ...
;     const int t = 16 * w + fr;
; #pragma unroll
;     for (int jn = 0; jn < 4; ++jn)
; #pragma unroll
;       for (int e = 0; e < 4; ++e) {
;         const int j = jn * 16 + 4 * fq + e, ch = layer * 256 + g * 64 + j;
;         const float r = sigm(ar[jn][e] + P.lru_ba[ch]), ig = sigm(ai[jn][e] + P.lru_bx[ch]);
;         const float lam = P.lru_lam[ch];
;         const float xe = __expf(-lam);
;         float m8; asm volatile("v_mov_b32 %0, 0xc1000000" : "=v"(m8));
;         const float la = m8 * r * (xe * (1.f - xe * (0.5f - xe * (1.f / 3.f))));
;         const float av = __expf(la);
;         const float y2 = 2.f * la;
;         const float om = -y2 * (1.f + y2 * (0.5f + y2 * ((1.f / 6.f) + y2 * ((1.f / 24.f) + y2 * ((1.f / 120.f) + y2 * (1.f / 720.f))))));
;         const float bv = sqrtf(om) * (ig * xcf[t * 65 + j]);
;         aA[t * 65 + j] = av; bB[t * 65 + j] = bv;
;       }
	v_mul_f32_e32 v43, 0xbfb8aa3b, v43
	v_exp_f32_e32 v43, v43
	s_nop 0
	v_fma_f32 v44, v43, s30, 0.5
	v_fma_f32 v44, -v43, v44, 1.0
	v_mul_f32_e32 v43, v43, v44
	v_mul_f32_e32 v29, v29, v43
	v_mul_f32_e32 v43, 0x3fb8aa3b, v29
	v_add_f32_e32 v29, v29, v29
	v_fmamk_f32 v44, v29, 0x3ab60b61, v213
	v_fmaak_f32 v44, v29, v44, 0x3d2aaaab
	v_fmaak_f32 v44, v29, v44, 0x3e2aaaab
	v_fma_f32 v44, v29, v44, 0.5
	v_fma_f32 v44, v29, v44, 1.0
	v_mul_f32_e64 v29, v44, -v29
	v_cmp_gt_f32_e32 vcc, s31, v29
	v_mul_f32_e32 v44, 0x4f800000, v29
	v_exp_f32_e32 v43, v43
	v_cndmask_b32_e32 v29, v29, v44, vcc
	v_sqrt_f32_e32 v44, v29
	s_nop 0
	v_add_u32_e32 v45, -1, v44
	v_fma_f32 v46, -v45, v44, v29
	v_cmp_ge_f32_e64 s[0:1], 0, v46
	v_add_u32_e32 v46, 1, v44
	s_nop 0
	v_cndmask_b32_e64 v45, v44, v45, s[0:1]
	v_fma_f32 v44, -v46, v44, v29
	v_cmp_lt_f32_e64 s[0:1], 0, v44
	s_nop 1
	v_cndmask_b32_e64 v44, v45, v46, s[0:1]
	v_mul_f32_e32 v45, 0x37800000, v44
	v_cndmask_b32_e32 v44, v44, v45, vcc
	v_cmp_class_f32_e32 vcc, v29, v214
	s_nop 1
	v_cndmask_b32_e32 v29, v44, v29, vcc
	ds_read_b32 v44, v24 offset:9220
	s_waitcnt lgkmcnt(0)
	v_mul_f32_e32 v25, v44, v25
	v_mul_f32_e32 v25, v25, v29
	v_add_u32_e32 v29, 4, v24
	ds_write2st64_b32 v29, v43, v25 offset0:101 offset1:166
	v_mov_b32_e32 v25, v86
	v_mov_b32_e32 v29, v102
	s_waitcnt vmcnt(1)
	v_add_f32_e32 v25, v30, v25
	s_waitcnt vmcnt(0)
	v_add_f32_e32 v26, v26, v29
	v_mov_b32_e32 v29, v118
	v_mul_f32_e32 v25, 0xbfb8aa3b, v25
	v_exp_f32_e32 v25, v25
	v_mov_b32 v30, 0xc1000000
	v_mul_f32_e32 v26, 0xbfb8aa3b, v26
	v_exp_f32_e32 v26, v26
	v_add_f32_e32 v25, 1.0, v25
	v_rcp_f32_e32 v25, v25
	v_add_f32_e32 v26, 1.0, v26
	v_rcp_f32_e32 v26, v26
	v_mul_f32_e32 v25, v30, v25
	s_waitcnt vmcnt(0)
	v_mul_f32_e32 v29, 0xbfb8aa3b, v29
	v_exp_f32_e32 v29, v29
	s_nop 0
	v_fma_f32 v30, v29, s30, 0.5
	v_fma_f32 v30, -v29, v30, 1.0
	v_mul_f32_e32 v29, v29, v30
	v_mul_f32_e32 v25, v25, v29
	v_mul_f32_e32 v29, 0x3fb8aa3b, v25
	v_add_f32_e32 v25, v25, v25
	v_fmamk_f32 v30, v25, 0x3ab60b61, v213
	v_fmaak_f32 v30, v25, v30, 0x3d2aaaab
	v_fmaak_f32 v30, v25, v30, 0x3e2aaaab
	v_fma_f32 v30, v25, v30, 0.5
	v_fma_f32 v30, v25, v30, 1.0
	v_mul_f32_e64 v25, v30, -v25
	v_cmp_gt_f32_e32 vcc, s31, v25
	v_mul_f32_e32 v30, 0x4f800000, v25
	v_exp_f32_e32 v29, v29
	v_cndmask_b32_e32 v25, v25, v30, vcc
	v_sqrt_f32_e32 v30, v25
	s_nop 0
	v_add_u32_e32 v43, -1, v30
	v_fma_f32 v44, -v43, v30, v25
	v_cmp_ge_f32_e64 s[0:1], 0, v44
	v_add_u32_e32 v44, 1, v30
	s_nop 0
	v_cndmask_b32_e64 v43, v30, v43, s[0:1]
	v_fma_f32 v30, -v44, v30, v25
	v_cmp_lt_f32_e64 s[0:1], 0, v30
	s_nop 1
	v_cndmask_b32_e64 v30, v43, v44, s[0:1]
	v_mul_f32_e32 v43, 0x37800000, v30
	v_cndmask_b32_e32 v30, v30, v43, vcc
	v_cmp_class_f32_e32 vcc, v25, v214
	s_nop 1
	v_cndmask_b32_e32 v25, v30, v25, vcc
	ds_read_b32 v30, v24 offset:9224
	s_waitcnt lgkmcnt(0)
	v_mul_f32_e32 v26, v30, v26
	v_mul_f32_e32 v25, v26, v25
	v_add_u32_e32 v26, 8, v24
	ds_write2st64_b32 v26, v29, v25 offset0:101 offset1:166
	v_mov_b32_e32 v25, v87
	v_mov_b32_e32 v26, v103
	s_waitcnt vmcnt(1)
	v_add_f32_e32 v25, v31, v25
	s_waitcnt vmcnt(0)
	v_add_f32_e32 v26, v27, v26
	v_mov_b32_e32 v27, v119
	v_mul_f32_e32 v25, 0xbfb8aa3b, v25
	v_exp_f32_e32 v25, v25
	v_mov_b32 v29, 0xc1000000
	v_mul_f32_e32 v26, 0xbfb8aa3b, v26
	v_exp_f32_e32 v26, v26
	v_add_f32_e32 v25, 1.0, v25
	v_rcp_f32_e32 v25, v25
	v_add_f32_e32 v26, 1.0, v26
	v_rcp_f32_e32 v26, v26
	v_mul_f32_e32 v25, v29, v25
	s_waitcnt vmcnt(0)
	v_mul_f32_e32 v27, 0xbfb8aa3b, v27
	v_exp_f32_e32 v27, v27
	s_nop 0
	v_fma_f32 v29, v27, s30, 0.5
	v_fma_f32 v29, -v27, v29, 1.0
	v_mul_f32_e32 v27, v27, v29
	v_mul_f32_e32 v25, v25, v27
	v_mul_f32_e32 v27, 0x3fb8aa3b, v25
	v_add_f32_e32 v25, v25, v25
	v_fmamk_f32 v29, v25, 0x3ab60b61, v213
	v_fmaak_f32 v29, v25, v29, 0x3d2aaaab
	v_fmaak_f32 v29, v25, v29, 0x3e2aaaab
	v_fma_f32 v29, v25, v29, 0.5
	v_fma_f32 v29, v25, v29, 1.0
	v_mul_f32_e64 v25, v29, -v25
	v_cmp_gt_f32_e32 vcc, s31, v25
	v_mul_f32_e32 v29, 0x4f800000, v25
	v_exp_f32_e32 v27, v27
	v_cndmask_b32_e32 v25, v25, v29, vcc
	v_sqrt_f32_e32 v29, v25
	s_nop 0
	v_add_u32_e32 v30, -1, v29
	v_fma_f32 v31, -v30, v29, v25
	v_cmp_ge_f32_e64 s[0:1], 0, v31
	v_add_u32_e32 v31, 1, v29
	s_nop 0
	v_cndmask_b32_e64 v30, v29, v30, s[0:1]
	v_fma_f32 v29, -v31, v29, v25
	v_cmp_lt_f32_e64 s[0:1], 0, v29
	s_nop 1
	v_cndmask_b32_e64 v29, v30, v31, s[0:1]
	v_mul_f32_e32 v30, 0x37800000, v29
	v_cndmask_b32_e32 v29, v29, v30, vcc
	v_cmp_class_f32_e32 vcc, v25, v214
	s_nop 1
	v_cndmask_b32_e32 v25, v29, v25, vcc
	ds_read_b32 v29, v24 offset:9228
	s_waitcnt lgkmcnt(0)
	v_mul_f32_e32 v26, v29, v26
	v_mul_f32_e32 v25, v26, v25
	v_add_u32_e32 v26, 12, v24
	ds_write2st64_b32 v26, v27, v25 offset0:101 offset1:166
	v_mov_b32_e32 v25, v88
	s_waitcnt vmcnt(0)
	v_add_f32_e32 v20, v20, v25
	v_mov_b32_e32 v25, v104
	v_mul_f32_e32 v20, 0xbfb8aa3b, v20
	v_exp_f32_e32 v20, v20
	s_waitcnt vmcnt(0)
	v_add_f32_e32 v16, v16, v25
	v_mov_b32_e32 v25, v120
	v_add_f32_e32 v20, 1.0, v20
	v_rcp_f32_e32 v20, v20
	v_mov_b32 v26, 0xc1000000
	v_mul_f32_e32 v16, 0xbfb8aa3b, v16
	v_exp_f32_e32 v16, v16
	v_mul_f32_e32 v20, v26, v20
	v_add_f32_e32 v16, 1.0, v16
	v_rcp_f32_e32 v16, v16
	s_waitcnt vmcnt(0)
; __device__ __forceinline__ float sigm(float x) { return __builtin_amdgcn_rcpf(1.f + __expf(-x)); }
; __device__ __forceinline__ void mixB1_item(const Params& P, int layer, int idx, const bf16_t* z, float* hsl, float* Pc, float* carryP, float* carryH, char* lds) {
;     ...
;     const int t = 16 * w + fr;
; #pragma unroll
;     for (int jn = 0; jn < 4; ++jn)
; #pragma unroll
;       for (int e = 0; e < 4; ++e) {
;         const int j = jn * 16 + 4 * fq + e, ch = layer * 256 + g * 64 + j;
;         const float r = sigm(ar[jn][e] + P.lru_ba[ch]), ig = sigm(ai[jn][e] + P.lru_bx[ch]);
;         const float lam = P.lru_lam[ch];
;         const float xe = __expf(-lam);
;         float m8; asm volatile("v_mov_b32 %0, 0xc1000000" : "=v"(m8));
;         const float la = m8 * r * (xe * (1.f - xe * (0.5f - xe * (1.f / 3.f))));
;         const float av = __expf(la);
;         const float y2 = 2.f * la;
;         const float om = -y2 * (1.f + y2 * (0.5f + y2 * ((1.f / 6.f) + y2 * ((1.f / 24.f) + y2 * ((1.f / 120.f) + y2 * (1.f / 720.f))))));
;         const float bv = sqrtf(om) * (ig * xcf[t * 65 + j]);
;         aA[t * 65 + j] = av; bB[t * 65 + j] = bv;
;       }
	v_mul_f32_e32 v25, 0xbfb8aa3b, v25
	v_exp_f32_e32 v25, v25
	s_nop 0
	v_fma_f32 v26, v25, s30, 0.5
	v_fma_f32 v26, -v25, v26, 1.0
	v_mul_f32_e32 v25, v25, v26
	v_mul_f32_e32 v20, v20, v25
	v_mul_f32_e32 v25, 0x3fb8aa3b, v20
	v_add_f32_e32 v20, v20, v20
	v_fmamk_f32 v26, v20, 0x3ab60b61, v213
	v_fmaak_f32 v26, v20, v26, 0x3d2aaaab
	v_fmaak_f32 v26, v20, v26, 0x3e2aaaab
	v_fma_f32 v26, v20, v26, 0.5
	v_fma_f32 v26, v20, v26, 1.0
	v_mul_f32_e64 v20, v26, -v20
	v_cmp_gt_f32_e32 vcc, s31, v20
	v_mul_f32_e32 v26, 0x4f800000, v20
	v_exp_f32_e32 v25, v25
	v_cndmask_b32_e32 v20, v20, v26, vcc
	v_sqrt_f32_e32 v26, v20
	s_nop 0
	v_add_u32_e32 v27, -1, v26
	v_fma_f32 v29, -v27, v26, v20
	v_cmp_ge_f32_e64 s[0:1], 0, v29
	v_add_u32_e32 v29, 1, v26
	s_nop 0
	v_cndmask_b32_e64 v27, v26, v27, s[0:1]
	v_fma_f32 v26, -v29, v26, v20
	v_cmp_lt_f32_e64 s[0:1], 0, v26
	s_nop 1
	v_cndmask_b32_e64 v26, v27, v29, s[0:1]
	v_mul_f32_e32 v27, 0x37800000, v26
	v_cndmask_b32_e32 v26, v26, v27, vcc
	v_cmp_class_f32_e32 vcc, v20, v214
	s_nop 1
	v_cndmask_b32_e32 v20, v26, v20, vcc
	ds_read_b32 v26, v24 offset:9280
	s_waitcnt lgkmcnt(0)
	v_mul_f32_e32 v16, v26, v16
	v_mul_f32_e32 v16, v16, v20
	v_add_u32_e32 v20, 64, v24
	ds_write2st64_b32 v20, v25, v16 offset0:101 offset1:166
	v_mov_b32_e32 v16, v89
	v_mov_b32_e32 v20, v105
	s_waitcnt vmcnt(1)
	v_add_f32_e32 v16, v21, v16
	s_waitcnt vmcnt(0)
	v_add_f32_e32 v17, v17, v20
	v_mov_b32_e32 v20, v121
	v_mul_f32_e32 v16, 0xbfb8aa3b, v16
	v_exp_f32_e32 v16, v16
	v_mov_b32 v21, 0xc1000000
	v_mul_f32_e32 v17, 0xbfb8aa3b, v17
	v_exp_f32_e32 v17, v17
	v_add_f32_e32 v16, 1.0, v16
	v_rcp_f32_e32 v16, v16
	v_add_f32_e32 v17, 1.0, v17
	v_rcp_f32_e32 v17, v17
	v_mul_f32_e32 v16, v21, v16
	s_waitcnt vmcnt(0)
	v_mul_f32_e32 v20, 0xbfb8aa3b, v20
	v_exp_f32_e32 v20, v20
	s_nop 0
	v_fma_f32 v21, v20, s30, 0.5
	v_fma_f32 v21, -v20, v21, 1.0
	v_mul_f32_e32 v20, v20, v21
	v_mul_f32_e32 v16, v16, v20
	v_mul_f32_e32 v20, 0x3fb8aa3b, v16
	v_add_f32_e32 v16, v16, v16
	v_fmamk_f32 v21, v16, 0x3ab60b61, v213
	v_fmaak_f32 v21, v16, v21, 0x3d2aaaab
	v_fmaak_f32 v21, v16, v21, 0x3e2aaaab
	v_fma_f32 v21, v16, v21, 0.5
	v_fma_f32 v21, v16, v21, 1.0
	v_mul_f32_e64 v16, v21, -v16
	v_cmp_gt_f32_e32 vcc, s31, v16
	v_mul_f32_e32 v21, 0x4f800000, v16
	v_exp_f32_e32 v20, v20
	v_cndmask_b32_e32 v16, v16, v21, vcc
	v_sqrt_f32_e32 v21, v16
	s_nop 0
	v_add_u32_e32 v25, -1, v21
	v_fma_f32 v26, -v25, v21, v16
	v_cmp_ge_f32_e64 s[0:1], 0, v26
	v_add_u32_e32 v26, 1, v21
	s_nop 0
	v_cndmask_b32_e64 v25, v21, v25, s[0:1]
	v_fma_f32 v21, -v26, v21, v16
	v_cmp_lt_f32_e64 s[0:1], 0, v21
	s_nop 1
	v_cndmask_b32_e64 v21, v25, v26, s[0:1]
	v_mul_f32_e32 v25, 0x37800000, v21
	v_cndmask_b32_e32 v21, v21, v25, vcc
	v_cmp_class_f32_e32 vcc, v16, v214
	s_nop 1
	v_cndmask_b32_e32 v16, v21, v16, vcc
	ds_read_b32 v21, v24 offset:9284
	s_waitcnt lgkmcnt(0)
	v_mul_f32_e32 v17, v21, v17
	v_mul_f32_e32 v16, v17, v16
	v_add_u32_e32 v17, 0x44, v24
	ds_write2st64_b32 v17, v20, v16 offset0:101 offset1:166
	v_mov_b32_e32 v16, v90
	v_mov_b32_e32 v17, v106
	s_waitcnt vmcnt(1)
	v_add_f32_e32 v16, v22, v16
	s_waitcnt vmcnt(0)
	v_add_f32_e32 v17, v18, v17
	v_mov_b32_e32 v18, v122
	v_mul_f32_e32 v16, 0xbfb8aa3b, v16
	v_exp_f32_e32 v16, v16
	v_mov_b32 v20, 0xc1000000
	v_mul_f32_e32 v17, 0xbfb8aa3b, v17
	v_exp_f32_e32 v17, v17
	v_add_f32_e32 v16, 1.0, v16
	v_rcp_f32_e32 v16, v16
	v_add_f32_e32 v17, 1.0, v17
	v_rcp_f32_e32 v17, v17
	v_mul_f32_e32 v16, v20, v16
	s_waitcnt vmcnt(0)
	v_mul_f32_e32 v18, 0xbfb8aa3b, v18
	v_exp_f32_e32 v18, v18
	s_nop 0
	v_fma_f32 v20, v18, s30, 0.5
	v_fma_f32 v20, -v18, v20, 1.0
	v_mul_f32_e32 v18, v18, v20
	v_mul_f32_e32 v16, v16, v18
	v_mul_f32_e32 v18, 0x3fb8aa3b, v16
	v_add_f32_e32 v16, v16, v16
	v_fmamk_f32 v20, v16, 0x3ab60b61, v213
	v_fmaak_f32 v20, v16, v20, 0x3d2aaaab
	v_fmaak_f32 v20, v16, v20, 0x3e2aaaab
	v_fma_f32 v20, v16, v20, 0.5
	v_fma_f32 v20, v16, v20, 1.0
	v_mul_f32_e64 v16, v20, -v16
	v_cmp_gt_f32_e32 vcc, s31, v16
	v_mul_f32_e32 v20, 0x4f800000, v16
	v_exp_f32_e32 v18, v18
	v_cndmask_b32_e32 v16, v16, v20, vcc
	v_sqrt_f32_e32 v20, v16
	s_nop 0
	v_add_u32_e32 v21, -1, v20
	v_fma_f32 v22, -v21, v20, v16
	v_cmp_ge_f32_e64 s[0:1], 0, v22
	v_add_u32_e32 v22, 1, v20
	s_nop 0
	v_cndmask_b32_e64 v21, v20, v21, s[0:1]
	v_fma_f32 v20, -v22, v20, v16
	v_cmp_lt_f32_e64 s[0:1], 0, v20
	s_nop 1
	v_cndmask_b32_e64 v20, v21, v22, s[0:1]
	v_mul_f32_e32 v21, 0x37800000, v20
	v_cndmask_b32_e32 v20, v20, v21, vcc
	v_cmp_class_f32_e32 vcc, v16, v214
	s_nop 1
	v_cndmask_b32_e32 v16, v20, v16, vcc
	ds_read_b32 v20, v24 offset:9288
	s_waitcnt lgkmcnt(0)
	v_mul_f32_e32 v17, v20, v17
	v_mul_f32_e32 v16, v17, v16
	v_add_u32_e32 v17, 0x48, v24
	ds_write2st64_b32 v17, v18, v16 offset0:101 offset1:166
	v_mov_b32_e32 v16, v91
	v_mov_b32_e32 v17, v107
	v_mov_b32_e32 v18, v123
	s_waitcnt vmcnt(2)
	v_add_f32_e32 v16, v23, v16
	v_mul_f32_e32 v16, 0xbfb8aa3b, v16
	v_exp_f32_e32 v16, v16
	s_waitcnt vmcnt(0)
	v_mul_f32_e32 v18, 0xbfb8aa3b, v18
	v_exp_f32_e32 v18, v18
	v_add_f32_e32 v17, v19, v17
	v_add_f32_e32 v16, 1.0, v16
	v_rcp_f32_e32 v16, v16
	v_mov_b32 v19, 0xc1000000
	v_mul_f32_e32 v17, 0xbfb8aa3b, v17
	v_exp_f32_e32 v17, v17
	v_mul_f32_e32 v16, v19, v16
	v_fma_f32 v19, v18, s30, 0.5
	v_fma_f32 v19, -v18, v19, 1.0
	v_mul_f32_e32 v18, v18, v19
	v_mul_f32_e32 v16, v16, v18
	v_mul_f32_e32 v18, 0x3fb8aa3b, v16
	v_add_f32_e32 v16, v16, v16
	v_fmamk_f32 v19, v16, 0x3ab60b61, v213
	v_fmaak_f32 v19, v16, v19, 0x3d2aaaab
	v_fmaak_f32 v19, v16, v19, 0x3e2aaaab
	v_fma_f32 v19, v16, v19, 0.5
	v_fma_f32 v19, v16, v19, 1.0
	v_mul_f32_e64 v16, v19, -v16
	v_cmp_gt_f32_e32 vcc, s31, v16
	v_mul_f32_e32 v19, 0x4f800000, v16
	v_add_f32_e32 v17, 1.0, v17
	v_cndmask_b32_e32 v16, v16, v19, vcc
	v_sqrt_f32_e32 v19, v16
	v_rcp_f32_e32 v17, v17
	v_exp_f32_e32 v18, v18
	v_add_u32_e32 v20, -1, v19
	v_fma_f32 v21, -v20, v19, v16
	v_cmp_ge_f32_e64 s[0:1], 0, v21
	v_add_u32_e32 v21, 1, v19
	s_nop 0
	v_cndmask_b32_e64 v20, v19, v20, s[0:1]
	v_fma_f32 v19, -v21, v19, v16
	v_cmp_lt_f32_e64 s[0:1], 0, v19
	s_nop 1
	v_cndmask_b32_e64 v19, v20, v21, s[0:1]
	v_mul_f32_e32 v20, 0x37800000, v19
	v_cndmask_b32_e32 v19, v19, v20, vcc
	v_cmp_class_f32_e32 vcc, v16, v214
	s_nop 1
	v_cndmask_b32_e32 v16, v19, v16, vcc
	ds_read_b32 v19, v24 offset:9292
	s_waitcnt lgkmcnt(0)
; __device__ __forceinline__ float sigm(float x) { return __builtin_amdgcn_rcpf(1.f + __expf(-x)); }
; __device__ __forceinline__ void mixB1_item(const Params& P, int layer, int idx, const bf16_t* z, float* hsl, float* Pc, float* carryP, float* carryH, char* lds) {
;     ...
;     const int t = 16 * w + fr;
; #pragma unroll
;     for (int jn = 0; jn < 4; ++jn)
; #pragma unroll
;       for (int e = 0; e < 4; ++e) {
;         const int j = jn * 16 + 4 * fq + e, ch = layer * 256 + g * 64 + j;
;         const float r = sigm(ar[jn][e] + P.lru_ba[ch]), ig = sigm(ai[jn][e] + P.lru_bx[ch]);
;         const float lam = P.lru_lam[ch];
;         const float xe = __expf(-lam);
;         float m8; asm volatile("v_mov_b32 %0, 0xc1000000" : "=v"(m8));
;         const float la = m8 * r * (xe * (1.f - xe * (0.5f - xe * (1.f / 3.f))));
;         const float av = __expf(la);
;         const float y2 = 2.f * la;
;         const float om = -y2 * (1.f + y2 * (0.5f + y2 * ((1.f / 6.f) + y2 * ((1.f / 24.f) + y2 * ((1.f / 120.f) + y2 * (1.f / 720.f))))));
;         const float bv = sqrtf(om) * (ig * xcf[t * 65 + j]);
;         aA[t * 65 + j] = av; bB[t * 65 + j] = bv;
;       }
	v_mul_f32_e32 v17, v19, v17
	v_mul_f32_e32 v16, v17, v16
	v_add_u32_e32 v17, 0x4c, v24
	ds_write2st64_b32 v17, v18, v16 offset0:101 offset1:166
	v_mov_b32_e32 v16, v92
	s_waitcnt vmcnt(0)
	v_add_f32_e32 v12, v12, v16
	v_mov_b32_e32 v16, v108
	v_mul_f32_e32 v12, 0xbfb8aa3b, v12
	v_exp_f32_e32 v12, v12
	s_waitcnt vmcnt(0)
	v_add_f32_e32 v8, v8, v16
	v_mov_b32_e32 v16, v124
	v_add_f32_e32 v12, 1.0, v12
	v_rcp_f32_e32 v12, v12
	v_mov_b32 v17, 0xc1000000
	v_mul_f32_e32 v8, 0xbfb8aa3b, v8
	v_exp_f32_e32 v8, v8
	v_mul_f32_e32 v12, v17, v12
	v_add_f32_e32 v8, 1.0, v8
	v_rcp_f32_e32 v8, v8
	s_waitcnt vmcnt(0)
	v_mul_f32_e32 v16, 0xbfb8aa3b, v16
	v_exp_f32_e32 v16, v16
	s_nop 0
	v_fma_f32 v17, v16, s30, 0.5
	v_fma_f32 v17, -v16, v17, 1.0
	v_mul_f32_e32 v16, v16, v17
	v_mul_f32_e32 v12, v12, v16
	v_mul_f32_e32 v16, 0x3fb8aa3b, v12
	v_add_f32_e32 v12, v12, v12
	v_fmamk_f32 v17, v12, 0x3ab60b61, v213
	v_fmaak_f32 v17, v12, v17, 0x3d2aaaab
	v_fmaak_f32 v17, v12, v17, 0x3e2aaaab
	v_fma_f32 v17, v12, v17, 0.5
	v_fma_f32 v17, v12, v17, 1.0
	v_mul_f32_e64 v12, v17, -v12
	v_cmp_gt_f32_e32 vcc, s31, v12
	v_mul_f32_e32 v17, 0x4f800000, v12
	v_exp_f32_e32 v16, v16
	v_cndmask_b32_e32 v12, v12, v17, vcc
	v_sqrt_f32_e32 v17, v12
	s_nop 0
	v_add_u32_e32 v18, -1, v17
	v_fma_f32 v19, -v18, v17, v12
	v_cmp_ge_f32_e64 s[0:1], 0, v19
	v_add_u32_e32 v19, 1, v17
	s_nop 0
	v_cndmask_b32_e64 v18, v17, v18, s[0:1]
	v_fma_f32 v17, -v19, v17, v12
	v_cmp_lt_f32_e64 s[0:1], 0, v17
	s_nop 1
	v_cndmask_b32_e64 v17, v18, v19, s[0:1]
	v_mul_f32_e32 v18, 0x37800000, v17
	v_cndmask_b32_e32 v17, v17, v18, vcc
	v_cmp_class_f32_e32 vcc, v12, v214
	s_nop 1
	v_cndmask_b32_e32 v12, v17, v12, vcc
	ds_read_b32 v17, v24 offset:9344
	s_waitcnt lgkmcnt(0)
	v_mul_f32_e32 v8, v17, v8
	v_mul_f32_e32 v8, v8, v12
	v_add_u32_e32 v12, 0x80, v24
	ds_write2st64_b32 v12, v16, v8 offset0:101 offset1:166
	v_mov_b32_e32 v8, v93
	v_mov_b32_e32 v12, v109
	s_waitcnt vmcnt(1)
	v_add_f32_e32 v8, v13, v8
	s_waitcnt vmcnt(0)
	v_add_f32_e32 v9, v9, v12
	v_mov_b32_e32 v12, v125
	v_mul_f32_e32 v8, 0xbfb8aa3b, v8
	v_exp_f32_e32 v8, v8
	v_mov_b32 v13, 0xc1000000
	v_mul_f32_e32 v9, 0xbfb8aa3b, v9
	v_exp_f32_e32 v9, v9
	v_add_f32_e32 v8, 1.0, v8
	v_rcp_f32_e32 v8, v8
	v_add_f32_e32 v9, 1.0, v9
	v_rcp_f32_e32 v9, v9
	v_mul_f32_e32 v8, v13, v8
	s_waitcnt vmcnt(0)
	v_mul_f32_e32 v12, 0xbfb8aa3b, v12
	v_exp_f32_e32 v12, v12
	s_nop 0
	v_fma_f32 v13, v12, s30, 0.5
	v_fma_f32 v13, -v12, v13, 1.0
	v_mul_f32_e32 v12, v12, v13
	v_mul_f32_e32 v8, v8, v12
	v_mul_f32_e32 v12, 0x3fb8aa3b, v8
	v_add_f32_e32 v8, v8, v8
	v_fmamk_f32 v13, v8, 0x3ab60b61, v213
	v_fmaak_f32 v13, v8, v13, 0x3d2aaaab
	v_fmaak_f32 v13, v8, v13, 0x3e2aaaab
	v_fma_f32 v13, v8, v13, 0.5
	v_fma_f32 v13, v8, v13, 1.0
	v_mul_f32_e64 v8, v13, -v8
	v_cmp_gt_f32_e32 vcc, s31, v8
	v_mul_f32_e32 v13, 0x4f800000, v8
	v_exp_f32_e32 v12, v12
	v_cndmask_b32_e32 v8, v8, v13, vcc
	v_sqrt_f32_e32 v13, v8
	s_nop 0
	v_add_u32_e32 v16, -1, v13
	v_fma_f32 v17, -v16, v13, v8
	v_cmp_ge_f32_e64 s[0:1], 0, v17
	v_add_u32_e32 v17, 1, v13
	s_nop 0
	v_cndmask_b32_e64 v16, v13, v16, s[0:1]
	v_fma_f32 v13, -v17, v13, v8
	v_cmp_lt_f32_e64 s[0:1], 0, v13
	s_nop 1
	v_cndmask_b32_e64 v13, v16, v17, s[0:1]
	v_mul_f32_e32 v16, 0x37800000, v13
	v_cndmask_b32_e32 v13, v13, v16, vcc
	v_cmp_class_f32_e32 vcc, v8, v214
	s_nop 1
	v_cndmask_b32_e32 v8, v13, v8, vcc
	ds_read_b32 v13, v24 offset:9348
	s_waitcnt lgkmcnt(0)
	v_mul_f32_e32 v9, v13, v9
	v_mul_f32_e32 v8, v9, v8
	v_add_u32_e32 v9, 0x84, v24
	ds_write2st64_b32 v9, v12, v8 offset0:101 offset1:166
	v_mov_b32_e32 v8, v94
	v_mov_b32_e32 v9, v110
	s_waitcnt vmcnt(1)
	v_add_f32_e32 v8, v14, v8
	s_waitcnt vmcnt(0)
	v_add_f32_e32 v9, v10, v9
	v_mov_b32_e32 v10, v126
	v_mul_f32_e32 v8, 0xbfb8aa3b, v8
	v_exp_f32_e32 v8, v8
	v_mov_b32 v12, 0xc1000000
	v_mul_f32_e32 v9, 0xbfb8aa3b, v9
	v_exp_f32_e32 v9, v9
	v_add_f32_e32 v8, 1.0, v8
	v_rcp_f32_e32 v8, v8
	v_add_f32_e32 v9, 1.0, v9
	v_rcp_f32_e32 v9, v9
	v_mul_f32_e32 v8, v12, v8
	s_waitcnt vmcnt(0)
	v_mul_f32_e32 v10, 0xbfb8aa3b, v10
	v_exp_f32_e32 v10, v10
	s_nop 0
	v_fma_f32 v12, v10, s30, 0.5
	v_fma_f32 v12, -v10, v12, 1.0
	v_mul_f32_e32 v10, v10, v12
	v_mul_f32_e32 v8, v8, v10
	v_mul_f32_e32 v10, 0x3fb8aa3b, v8
	v_add_f32_e32 v8, v8, v8
	v_fmamk_f32 v12, v8, 0x3ab60b61, v213
	v_fmaak_f32 v12, v8, v12, 0x3d2aaaab
	v_fmaak_f32 v12, v8, v12, 0x3e2aaaab
	v_fma_f32 v12, v8, v12, 0.5
	v_fma_f32 v12, v8, v12, 1.0
	v_mul_f32_e64 v8, v12, -v8
	v_cmp_gt_f32_e32 vcc, s31, v8
	v_mul_f32_e32 v12, 0x4f800000, v8
	v_exp_f32_e32 v10, v10
	v_cndmask_b32_e32 v8, v8, v12, vcc
	v_sqrt_f32_e32 v12, v8
	s_nop 0
	v_add_u32_e32 v13, -1, v12
	v_fma_f32 v14, -v13, v12, v8
	v_cmp_ge_f32_e64 s[0:1], 0, v14
	v_add_u32_e32 v14, 1, v12
	s_nop 0
	v_cndmask_b32_e64 v13, v12, v13, s[0:1]
	v_fma_f32 v12, -v14, v12, v8
	v_cmp_lt_f32_e64 s[0:1], 0, v12
	s_nop 1
	v_cndmask_b32_e64 v12, v13, v14, s[0:1]
	v_mul_f32_e32 v13, 0x37800000, v12
	v_cndmask_b32_e32 v12, v12, v13, vcc
	v_cmp_class_f32_e32 vcc, v8, v214
	s_nop 1
	v_cndmask_b32_e32 v8, v12, v8, vcc
	ds_read_b32 v12, v24 offset:9352
	s_waitcnt lgkmcnt(0)
	v_mul_f32_e32 v9, v12, v9
	v_mul_f32_e32 v8, v9, v8
	v_add_u32_e32 v9, 0x88, v24
	ds_write2st64_b32 v9, v10, v8 offset0:101 offset1:166
	v_mov_b32_e32 v8, v95
	v_mov_b32_e32 v9, v111
	v_mov_b32_e32 v10, v127
	s_waitcnt vmcnt(2)
	v_add_f32_e32 v8, v15, v8
	v_mul_f32_e32 v8, 0xbfb8aa3b, v8
	v_exp_f32_e32 v8, v8
	s_waitcnt vmcnt(0)
; __device__ __forceinline__ float sigm(float x) { return __builtin_amdgcn_rcpf(1.f + __expf(-x)); }
; __device__ __forceinline__ void mixB1_item(const Params& P, int layer, int idx, const bf16_t* z, float* hsl, float* Pc, float* carryP, float* carryH, char* lds) {
;     ...
;     const int t = 16 * w + fr;
; #pragma unroll
;     for (int jn = 0; jn < 4; ++jn)
; #pragma unroll
;       for (int e = 0; e < 4; ++e) {
;         const int j = jn * 16 + 4 * fq + e, ch = layer * 256 + g * 64 + j;
;         const float r = sigm(ar[jn][e] + P.lru_ba[ch]), ig = sigm(ai[jn][e] + P.lru_bx[ch]);
;         const float lam = P.lru_lam[ch];
;         const float xe = __expf(-lam);
;         float m8; asm volatile("v_mov_b32 %0, 0xc1000000" : "=v"(m8));
;         const float la = m8 * r * (xe * (1.f - xe * (0.5f - xe * (1.f / 3.f))));
;         const float av = __expf(la);
;         const float y2 = 2.f * la;
;         const float om = -y2 * (1.f + y2 * (0.5f + y2 * ((1.f / 6.f) + y2 * ((1.f / 24.f) + y2 * ((1.f / 120.f) + y2 * (1.f / 720.f))))));
;         const float bv = sqrtf(om) * (ig * xcf[t * 65 + j]);
;         aA[t * 65 + j] = av; bB[t * 65 + j] = bv;
;       }
	v_mul_f32_e32 v10, 0xbfb8aa3b, v10
	v_exp_f32_e32 v10, v10
	v_add_f32_e32 v9, v11, v9
	v_add_f32_e32 v8, 1.0, v8
	v_rcp_f32_e32 v8, v8
	v_mov_b32 v11, 0xc1000000
	v_mul_f32_e32 v9, 0xbfb8aa3b, v9
	v_exp_f32_e32 v9, v9
	v_mul_f32_e32 v8, v11, v8
	v_fma_f32 v11, v10, s30, 0.5
	v_fma_f32 v11, -v10, v11, 1.0
	v_mul_f32_e32 v10, v10, v11
	v_mul_f32_e32 v8, v8, v10
	v_mul_f32_e32 v10, 0x3fb8aa3b, v8
	v_add_f32_e32 v8, v8, v8
	v_fmamk_f32 v11, v8, 0x3ab60b61, v213
	v_fmaak_f32 v11, v8, v11, 0x3d2aaaab
	v_fmaak_f32 v11, v8, v11, 0x3e2aaaab
	v_fma_f32 v11, v8, v11, 0.5
	v_fma_f32 v11, v8, v11, 1.0
	v_mul_f32_e64 v8, v11, -v8
	v_cmp_gt_f32_e32 vcc, s31, v8
	v_mul_f32_e32 v11, 0x4f800000, v8
	v_add_f32_e32 v9, 1.0, v9
	v_cndmask_b32_e32 v8, v8, v11, vcc
	v_sqrt_f32_e32 v11, v8
	v_rcp_f32_e32 v9, v9
	v_exp_f32_e32 v10, v10
	v_add_u32_e32 v12, -1, v11
	v_fma_f32 v13, -v12, v11, v8
	v_cmp_ge_f32_e64 s[0:1], 0, v13
	v_add_u32_e32 v13, 1, v11
	s_nop 0
	v_cndmask_b32_e64 v12, v11, v12, s[0:1]
	v_fma_f32 v11, -v13, v11, v8
	v_cmp_lt_f32_e64 s[0:1], 0, v11
	s_nop 1
	v_cndmask_b32_e64 v11, v12, v13, s[0:1]
	v_mul_f32_e32 v12, 0x37800000, v11
	v_cndmask_b32_e32 v11, v11, v12, vcc
	v_cmp_class_f32_e32 vcc, v8, v214
	s_nop 1
	v_cndmask_b32_e32 v8, v11, v8, vcc
	ds_read_b32 v11, v24 offset:9356
	s_waitcnt lgkmcnt(0)
	v_mul_f32_e32 v9, v11, v9
	v_mul_f32_e32 v8, v9, v8
	v_add_u32_e32 v9, 0x8c, v24
	ds_write2st64_b32 v9, v10, v8 offset0:101 offset1:166
	v_mov_b32_e32 v8, v96
	s_waitcnt vmcnt(0)
	v_add_f32_e32 v4, v4, v8
	v_mov_b32_e32 v8, v112
	v_mul_f32_e32 v4, 0xbfb8aa3b, v4
	v_exp_f32_e32 v4, v4
	s_waitcnt vmcnt(0)
	v_add_f32_e32 v0, v0, v8
	v_mov_b32_e32 v8, v128
	v_add_f32_e32 v4, 1.0, v4
	v_rcp_f32_e32 v4, v4
	v_mov_b32 v9, 0xc1000000
	v_mul_f32_e32 v0, 0xbfb8aa3b, v0
	v_exp_f32_e32 v0, v0
	v_mul_f32_e32 v4, v9, v4
	v_add_f32_e32 v0, 1.0, v0
	v_rcp_f32_e32 v0, v0
	s_waitcnt vmcnt(0)
	v_mul_f32_e32 v8, 0xbfb8aa3b, v8
	v_exp_f32_e32 v8, v8
	s_nop 0
	v_fma_f32 v9, v8, s30, 0.5
	v_fma_f32 v9, -v8, v9, 1.0
	v_mul_f32_e32 v8, v8, v9
	v_mul_f32_e32 v4, v4, v8
	v_mul_f32_e32 v8, 0x3fb8aa3b, v4
	v_add_f32_e32 v4, v4, v4
	v_fmamk_f32 v9, v4, 0x3ab60b61, v213
	v_fmaak_f32 v9, v4, v9, 0x3d2aaaab
	v_fmaak_f32 v9, v4, v9, 0x3e2aaaab
	v_fma_f32 v9, v4, v9, 0.5
	v_fma_f32 v9, v4, v9, 1.0
	v_mul_f32_e64 v4, v9, -v4
	v_cmp_gt_f32_e32 vcc, s31, v4
	v_mul_f32_e32 v9, 0x4f800000, v4
	v_exp_f32_e32 v8, v8
	v_cndmask_b32_e32 v4, v4, v9, vcc
	v_sqrt_f32_e32 v9, v4
	s_nop 0
	v_add_u32_e32 v10, -1, v9
	v_fma_f32 v11, -v10, v9, v4
	v_cmp_ge_f32_e64 s[0:1], 0, v11
	v_add_u32_e32 v11, 1, v9
	s_nop 0
	v_cndmask_b32_e64 v10, v9, v10, s[0:1]
	v_fma_f32 v9, -v11, v9, v4
	v_cmp_lt_f32_e64 s[0:1], 0, v9
	s_nop 1
	v_cndmask_b32_e64 v9, v10, v11, s[0:1]
	v_mul_f32_e32 v10, 0x37800000, v9
	v_cndmask_b32_e32 v9, v9, v10, vcc
	v_cmp_class_f32_e32 vcc, v4, v214
	s_nop 1
	v_cndmask_b32_e32 v4, v9, v4, vcc
	ds_read_b32 v9, v24 offset:9408
	s_waitcnt lgkmcnt(0)
	v_mul_f32_e32 v0, v9, v0
	v_mul_f32_e32 v0, v0, v4
	v_add_u32_e32 v4, 0xc0, v24
	ds_write2st64_b32 v4, v8, v0 offset0:101 offset1:166
	v_mov_b32_e32 v0, v97
	v_mov_b32_e32 v4, v113
	s_waitcnt vmcnt(1)
	v_add_f32_e32 v0, v5, v0
	s_waitcnt vmcnt(0)
	v_add_f32_e32 v1, v1, v4
	v_mov_b32_e32 v4, v129
	v_mul_f32_e32 v0, 0xbfb8aa3b, v0
	v_exp_f32_e32 v0, v0
	v_mov_b32 v5, 0xc1000000
	v_mul_f32_e32 v1, 0xbfb8aa3b, v1
	v_exp_f32_e32 v1, v1
	v_add_f32_e32 v0, 1.0, v0
	v_rcp_f32_e32 v0, v0
	v_add_f32_e32 v1, 1.0, v1
	v_rcp_f32_e32 v1, v1
	v_mul_f32_e32 v0, v5, v0
	s_waitcnt vmcnt(0)
	v_mul_f32_e32 v4, 0xbfb8aa3b, v4
	v_exp_f32_e32 v4, v4
	s_nop 0
	v_fma_f32 v5, v4, s30, 0.5
	v_fma_f32 v5, -v4, v5, 1.0
	v_mul_f32_e32 v4, v4, v5
	v_mul_f32_e32 v0, v0, v4
	v_mul_f32_e32 v4, 0x3fb8aa3b, v0
	v_add_f32_e32 v0, v0, v0
	v_fmamk_f32 v5, v0, 0x3ab60b61, v213
	v_fmaak_f32 v5, v0, v5, 0x3d2aaaab
	v_fmaak_f32 v5, v0, v5, 0x3e2aaaab
	v_fma_f32 v5, v0, v5, 0.5
	v_fma_f32 v5, v0, v5, 1.0
	v_mul_f32_e64 v0, v5, -v0
	v_cmp_gt_f32_e32 vcc, s31, v0
	v_mul_f32_e32 v5, 0x4f800000, v0
	v_exp_f32_e32 v4, v4
	v_cndmask_b32_e32 v0, v0, v5, vcc
	v_sqrt_f32_e32 v5, v0
	s_nop 0
	v_add_u32_e32 v8, -1, v5
	v_fma_f32 v9, -v8, v5, v0
	v_cmp_ge_f32_e64 s[0:1], 0, v9
	v_add_u32_e32 v9, 1, v5
	s_nop 0
	v_cndmask_b32_e64 v8, v5, v8, s[0:1]
	v_fma_f32 v5, -v9, v5, v0
	v_cmp_lt_f32_e64 s[0:1], 0, v5
	s_nop 1
	v_cndmask_b32_e64 v5, v8, v9, s[0:1]
	v_mul_f32_e32 v8, 0x37800000, v5
	v_cndmask_b32_e32 v5, v5, v8, vcc
	v_cmp_class_f32_e32 vcc, v0, v214
	s_nop 1
	v_cndmask_b32_e32 v0, v5, v0, vcc
	ds_read_b32 v5, v24 offset:9412
	s_waitcnt lgkmcnt(0)
	v_mul_f32_e32 v1, v5, v1
	v_mul_f32_e32 v0, v1, v0
	v_add_u32_e32 v1, 0xc4, v24
	ds_write2st64_b32 v1, v4, v0 offset0:101 offset1:166
	v_mov_b32_e32 v0, v98
	v_mov_b32_e32 v1, v114
	s_waitcnt vmcnt(1)
	v_add_f32_e32 v0, v6, v0
	s_waitcnt vmcnt(0)
	v_add_f32_e32 v1, v2, v1
	v_mov_b32_e32 v2, v130
	v_mul_f32_e32 v0, 0xbfb8aa3b, v0
	v_exp_f32_e32 v0, v0
	v_mov_b32 v4, 0xc1000000
	v_mul_f32_e32 v1, 0xbfb8aa3b, v1
	v_exp_f32_e32 v1, v1
	v_add_f32_e32 v0, 1.0, v0
	v_rcp_f32_e32 v0, v0
	v_add_f32_e32 v1, 1.0, v1
	v_rcp_f32_e32 v1, v1
	v_mul_f32_e32 v0, v4, v0
	s_waitcnt vmcnt(0)
; __device__ __forceinline__ float sigm(float x) { return __builtin_amdgcn_rcpf(1.f + __expf(-x)); }
; __device__ __forceinline__ void mixB1_item(const Params& P, int layer, int idx, const bf16_t* z, float* hsl, float* Pc, float* carryP, float* carryH, char* lds) {
;     ...
;       for (int e = 0; e < 4; ++e) {
;         const int j = jn * 16 + 4 * fq + e, ch = layer * 256 + g * 64 + j;
;         const float r = sigm(ar[jn][e] + P.lru_ba[ch]), ig = sigm(ai[jn][e] + P.lru_bx[ch]);
;         const float lam = P.lru_lam[ch];
;         const float xe = __expf(-lam);
;         float m8; asm volatile("v_mov_b32 %0, 0xc1000000" : "=v"(m8));
;         const float la = m8 * r * (xe * (1.f - xe * (0.5f - xe * (1.f / 3.f))));
;         const float av = __expf(la);
;         const float y2 = 2.f * la;
;         const float om = -y2 * (1.f + y2 * (0.5f + y2 * ((1.f / 6.f) + y2 * ((1.f / 24.f) + y2 * ((1.f / 120.f) + y2 * (1.f / 720.f))))));
;         const float bv = sqrtf(om) * (ig * xcf[t * 65 + j]);
;         aA[t * 65 + j] = av; bB[t * 65 + j] = bv;
;       }
;   }
;   __syncthreads();
;   {
;     const int q = tid >> 6, j = tid & 63;
;     float Pq = 1.f, hq = 0.f;
; #pragma unroll
;     for (int i = 0; i < 16; ++i) { const int t = q * 16 + i; const float av = aA[t * 65 + j], bv = bB[t * 65 + j]; hq = av * hq + bv; Pq *= av; aA[t * 65 + j] = Pq; bB[t * 65 + j] = hq; }
;     sm[q * 64 + j] = Pq; sm[256 + q * 64 + j] = hq;
;     __syncthreads();
;     float Pin = 1.f, Hin = 0.f;
;     for (int qq = 0; qq < q; ++qq) { const float pp = sm[qq * 64 + j], hh = sm[256 + qq * 64 + j]; Hin = pp * Hin + hh; Pin *= pp; }
	v_mul_f32_e32 v2, 0xbfb8aa3b, v2
	v_exp_f32_e32 v2, v2
	s_nop 0
	v_fma_f32 v4, v2, s30, 0.5
	v_fma_f32 v4, -v2, v4, 1.0
	v_mul_f32_e32 v2, v2, v4
	v_mul_f32_e32 v0, v0, v2
	v_mul_f32_e32 v2, 0x3fb8aa3b, v0
	v_add_f32_e32 v0, v0, v0
	v_fmamk_f32 v4, v0, 0x3ab60b61, v213
	v_fmaak_f32 v4, v0, v4, 0x3d2aaaab
	v_fmaak_f32 v4, v0, v4, 0x3e2aaaab
	v_fma_f32 v4, v0, v4, 0.5
	v_fma_f32 v4, v0, v4, 1.0
	v_mul_f32_e64 v0, v4, -v0
	v_cmp_gt_f32_e32 vcc, s31, v0
	v_mul_f32_e32 v4, 0x4f800000, v0
	v_exp_f32_e32 v2, v2
	v_cndmask_b32_e32 v0, v0, v4, vcc
	v_sqrt_f32_e32 v4, v0
	s_nop 0
	v_add_u32_e32 v5, -1, v4
	v_fma_f32 v6, -v5, v4, v0
	v_cmp_ge_f32_e64 s[0:1], 0, v6
	v_add_u32_e32 v6, 1, v4
	s_nop 0
	v_cndmask_b32_e64 v5, v4, v5, s[0:1]
	v_fma_f32 v4, -v6, v4, v0
	v_cmp_lt_f32_e64 s[0:1], 0, v4
	s_nop 1
	v_cndmask_b32_e64 v4, v5, v6, s[0:1]
	v_mul_f32_e32 v5, 0x37800000, v4
	v_cndmask_b32_e32 v4, v4, v5, vcc
	v_cmp_class_f32_e32 vcc, v0, v214
	s_nop 1
	v_cndmask_b32_e32 v0, v4, v0, vcc
	ds_read_b32 v4, v24 offset:9416
	s_waitcnt lgkmcnt(0)
	v_mul_f32_e32 v1, v4, v1
	v_mul_f32_e32 v0, v1, v0
	v_add_u32_e32 v1, 0xc8, v24
	ds_write2st64_b32 v1, v2, v0 offset0:101 offset1:166
	v_mov_b32_e32 v0, v99
	v_mov_b32_e32 v1, v115
	v_mov_b32_e32 v2, v131
	s_waitcnt vmcnt(2)
	v_add_f32_e32 v0, v7, v0
	v_mul_f32_e32 v0, 0xbfb8aa3b, v0
	v_exp_f32_e32 v0, v0
	s_waitcnt vmcnt(0)
	v_mul_f32_e32 v2, 0xbfb8aa3b, v2
	v_exp_f32_e32 v2, v2
	v_add_f32_e32 v1, v3, v1
	v_add_f32_e32 v0, 1.0, v0
	v_rcp_f32_e32 v0, v0
	v_mov_b32 v3, 0xc1000000
	v_mul_f32_e32 v1, 0xbfb8aa3b, v1
	v_exp_f32_e32 v1, v1
	v_mul_f32_e32 v0, v3, v0
	v_fma_f32 v3, v2, s30, 0.5
	v_fma_f32 v3, -v2, v3, 1.0
	v_mul_f32_e32 v2, v2, v3
	v_mul_f32_e32 v0, v0, v2
	v_mul_f32_e32 v2, 0x3fb8aa3b, v0
	v_add_f32_e32 v0, v0, v0
	v_fmamk_f32 v3, v0, 0x3ab60b61, v213
	v_fmaak_f32 v3, v0, v3, 0x3d2aaaab
	v_fmaak_f32 v3, v0, v3, 0x3e2aaaab
	v_fma_f32 v3, v0, v3, 0.5
	v_fma_f32 v3, v0, v3, 1.0
	v_mul_f32_e64 v0, v3, -v0
	v_cmp_gt_f32_e32 vcc, s31, v0
	v_mul_f32_e32 v3, 0x4f800000, v0
	v_add_f32_e32 v1, 1.0, v1
	v_cndmask_b32_e32 v0, v0, v3, vcc
	v_sqrt_f32_e32 v3, v0
	v_rcp_f32_e32 v1, v1
	v_exp_f32_e32 v2, v2
	v_add_u32_e32 v4, -1, v3
	v_fma_f32 v5, -v4, v3, v0
	v_cmp_ge_f32_e64 s[0:1], 0, v5
	v_add_u32_e32 v5, 1, v3
	s_nop 0
	v_cndmask_b32_e64 v4, v3, v4, s[0:1]
	v_fma_f32 v3, -v5, v3, v0
	v_cmp_lt_f32_e64 s[0:1], 0, v3
	s_nop 1
	v_cndmask_b32_e64 v3, v4, v5, s[0:1]
	v_mul_f32_e32 v4, 0x37800000, v3
	v_cndmask_b32_e32 v3, v3, v4, vcc
	v_cmp_class_f32_e32 vcc, v0, v214
	s_movk_i32 s0, 0x410
	s_nop 0
	v_cndmask_b32_e32 v0, v3, v0, vcc
	ds_read_b32 v3, v24 offset:9420
	v_cmp_lt_u32_e32 vcc, 63, v40
	s_waitcnt lgkmcnt(0)
	v_mul_f32_e32 v1, v3, v1
	v_mul_f32_e32 v0, v1, v0
	v_add_u32_e32 v1, 0xcc, v24
	ds_write2st64_b32 v1, v2, v0 offset0:101 offset1:166
	v_mad_u32_u24 v0, v39, s0, v38
	v_lshl_add_u32 v2, v0, 2, v60
	v_add_u32_e32 v3, 0x6400, v2
	v_add_u32_e32 v6, 0xa400, v2
	s_waitcnt lgkmcnt(0)
	s_barrier
	ds_read2_b32 v[0:1], v3 offset0:64 offset1:129
	ds_read2_b32 v[4:5], v6 offset0:128 offset1:193
	v_add_u32_e32 v9, 0xa800, v2
	s_waitcnt lgkmcnt(1)
	v_mul_f32_e32 v8, v0, v1
	s_waitcnt lgkmcnt(0)
	v_fma_f32 v4, 0, v0, v4
	v_fmac_f32_e32 v5, v4, v1
	v_add_u32_e32 v0, 0x6600, v2
	ds_write2_b32 v6, v4, v5 offset0:128 offset1:193
	ds_read2_b32 v[0:1], v0 offset0:66 offset1:131
	ds_read2_b32 v[6:7], v9 offset0:2 offset1:67
	s_waitcnt lgkmcnt(0)
	v_fma_f32 v4, v5, v0, v6
	v_mul_f32_e32 v0, v8, v0
	v_fmac_f32_e32 v7, v4, v1
	ds_write2_b32 v3, v8, v0 offset0:129 offset1:194
	ds_write2_b32 v9, v4, v7 offset0:2 offset1:67
	v_add_u32_e32 v8, 0x6800, v2
	v_mul_f32_e32 v3, v0, v1
	ds_read2_b32 v[0:1], v8 offset0:68 offset1:133
	ds_read2_b32 v[4:5], v9 offset0:132 offset1:197
	s_waitcnt lgkmcnt(0)
	v_fma_f32 v4, v7, v0, v4
	v_mul_f32_e32 v0, v3, v0
	v_fmac_f32_e32 v5, v4, v1
	ds_write2_b32 v8, v3, v0 offset0:3 offset1:68
	v_mul_f32_e32 v3, v0, v1
	ds_write2_b32 v9, v4, v5 offset0:132 offset1:197
	v_add_u32_e32 v0, 0x6a00, v2
	v_add_u32_e32 v9, 0xac00, v2
	ds_read2_b32 v[0:1], v0 offset0:70 offset1:135
	ds_read2_b32 v[6:7], v9 offset0:6 offset1:71
	s_waitcnt lgkmcnt(0)
	v_fma_f32 v4, v5, v0, v6
	v_mul_f32_e32 v0, v3, v0
	v_fmac_f32_e32 v7, v4, v1
	ds_write2_b32 v8, v3, v0 offset0:133 offset1:198
	ds_write2_b32 v9, v4, v7 offset0:6 offset1:71
	v_add_u32_e32 v8, 0x6c00, v2
	v_mul_f32_e32 v3, v0, v1
	ds_read2_b32 v[0:1], v8 offset0:72 offset1:137
	ds_read2_b32 v[4:5], v9 offset0:136 offset1:201
	s_waitcnt lgkmcnt(0)
	v_fma_f32 v4, v7, v0, v4
	v_mul_f32_e32 v0, v3, v0
	v_fmac_f32_e32 v5, v4, v1
	ds_write2_b32 v8, v3, v0 offset0:7 offset1:72
	v_mul_f32_e32 v3, v0, v1
	ds_write2_b32 v9, v4, v5 offset0:136 offset1:201
	v_add_u32_e32 v0, 0x6e00, v2
	v_add_u32_e32 v9, 0xb000, v2
	ds_read2_b32 v[0:1], v0 offset0:74 offset1:139
	ds_read2_b32 v[6:7], v9 offset0:10 offset1:75
	s_waitcnt lgkmcnt(0)
	v_fma_f32 v4, v5, v0, v6
	v_mul_f32_e32 v0, v3, v0
	v_fmac_f32_e32 v7, v4, v1
	ds_write2_b32 v8, v3, v0 offset0:137 offset1:202
	ds_write2_b32 v9, v4, v7 offset0:10 offset1:75
	v_add_u32_e32 v8, 0x7000, v2
	v_mul_f32_e32 v3, v0, v1
	ds_read2_b32 v[4:5], v8 offset0:76 offset1:141
	ds_read2_b32 v[0:1], v9 offset0:140 offset1:205
	s_waitcnt lgkmcnt(0)
	v_fma_f32 v0, v7, v4, v0
	v_fmac_f32_e32 v1, v0, v5
	v_mul_f32_e32 v4, v3, v4
	ds_write2_b32 v9, v0, v1 offset0:140 offset1:205
	v_add_u32_e32 v0, 0x7200, v2
	ds_write2_b32 v8, v3, v4 offset0:11 offset1:76
	v_mul_f32_e32 v3, v4, v5
	ds_read2_b32 v[4:5], v0 offset0:78 offset1:143
	v_add_u32_e32 v0, 0xb400, v2
	ds_read2_b32 v[6:7], v0 offset0:14 offset1:79
	s_waitcnt lgkmcnt(0)
	v_fma_f32 v1, v1, v4, v6
	v_mul_f32_e32 v4, v3, v4
	ds_write2_b32 v8, v3, v4 offset0:141 offset1:206
	v_mul_f32_e32 v3, v4, v5
	v_fmac_f32_e32 v7, v1, v5
	ds_write_b32 v2, v3 offset:29756
	ds_write2_b32 v0, v1, v7 offset0:14 offset1:79
	v_lshl_add_u32 v0, v40, 2, v60
	v_mov_b32_e32 v1, 0
	ds_write2st64_b32 v0, v3, v7 offset0:231 offset1:235
	s_waitcnt lgkmcnt(0)
	s_barrier
	s_and_saveexec_b64 s[0:1], vcc
	s_cbranch_execz .LBB0_566
	v_lshl_add_u32 v3, v38, 2, v34
	v_mov_b32_e32 v28, 1.0
	v_mov_b32_e32 v1, 0
	s_mov_b64 s[30:31], 0
	v_mov_b32_e32 v4, v39
